# FFN tile table: 8 expert counters read once together (were 24 serialized reads); GU unit head: accumulators cleared while the expert-list loads are in flight
# baseline (speedup 1.0000x reference)
; #define LAS __attribute__((address_space(3)))
; __device__ __forceinline__ int opaque_tid() { int t = threadIdx.x; asm volatile("" : "+v"(t)); return t; }
; __global__ void __launch_bounds__(NTHR, 2) fwd_kernel(Args args) {
;     ...
;             if (moe) {
;                 int tot = 0;
; #pragma unroll
;                 for (int e = 0; e < NE; ++e) { const int c = (int)__hip_atomic_load((unsigned*)(F.ctl + CW_CNT + (jm * 8 + e) * 64), RLX_AGENT); tot += (c + 255) >> 8; }
;                 ntiles = __builtin_amdgcn_readfirstlane(tot);
;                 __syncthreads();
;                 for (int T = opaque_tid(); T < ntiles; T += NTHR) {
;                     int acc_t = 0, me = 0, mpe = 0, mc = 0;
; #pragma unroll
;                     for (int e = 0; e < NE; ++e) { const int c = (int)__hip_atomic_load((unsigned*)(F.ctl + CW_CNT + (jm * 8 + e) * 64), RLX_AGENT);
;                         if (acc_t <= T) { me = e; mpe = acc_t; mc = c; } acc_t += (c + 255) >> 8; }
;                     const int aux = (T - mpe) * 256; const int left = mc - aux; const int cnt = left < 256 ? left : 256;
;                     ((LAS int*)(F.lds + gm::TILE_TAB_OFF))[2 * T] = me | (cnt << 4); ((LAS int*)(F.lds + gm::TILE_TAB_OFF))[2 * T + 1] = aux;
;                 }
;                 __syncthreads();
;             }
.LBB0_925:
	s_cmp_eq_u32 s5, 0
	s_cselect_b64 s[76:77], -1, 0
	s_cmp_lg_u32 s5, 0
	s_cselect_b64 s[46:47], -1, 0
	s_and_b64 vcc, exec, s[76:77]
	s_cbranch_vccnz .LBB0_930
	s_lshl_b32 s16, s4, 9
	s_lshl_b64 s[0:1], s[16:17], 2
	v_readlane_b32 s4, v254, 51
	v_readlane_b32 s5, v254, 52
	s_add_u32 s0, s4, s0
	s_addc_u32 s1, s5, s1
	global_load_dword v12, v67, s[0:1] sc1
	global_load_dword v13, v67, s[0:1] offset:256 sc1
	global_load_dword v14, v67, s[0:1] offset:512 sc1
	global_load_dword v15, v67, s[0:1] offset:768 sc1
	global_load_dword v16, v67, s[0:1] offset:1024 sc1
	global_load_dword v17, v67, s[0:1] offset:1280 sc1
	global_load_dword v18, v67, s[0:1] offset:1536 sc1
	global_load_dword v19, v67, s[0:1] offset:1792 sc1
	s_waitcnt vmcnt(0)
	v_mov_b32_e32 v2, v12
	v_mov_b32_e32 v3, v13
	v_add_u32_e32 v2, 0xff, v2
	v_add_u32_e32 v3, 0xff, v3
	v_ashrrev_i32_e32 v2, 8, v2
	v_ashrrev_i32_e32 v3, 8, v3
	v_add_u32_e32 v2, v3, v2
	v_mov_b32_e32 v3, v14
	v_add_u32_e32 v3, 0xff, v3
	v_ashrrev_i32_e32 v3, 8, v3
	v_add_u32_e32 v2, v3, v2
	v_mov_b32_e32 v3, v15
	v_add_u32_e32 v3, 0xff, v3
	v_ashrrev_i32_e32 v3, 8, v3
	v_add_u32_e32 v2, v3, v2
	v_mov_b32_e32 v3, v16
	v_add_u32_e32 v3, 0xff, v3
	v_ashrrev_i32_e32 v3, 8, v3
	v_add_u32_e32 v2, v3, v2
	v_mov_b32_e32 v3, v17
	v_add_u32_e32 v3, 0xff, v3
	v_ashrrev_i32_e32 v3, 8, v3
	v_add_u32_e32 v2, v3, v2
	v_mov_b32_e32 v3, v18
	v_add_u32_e32 v3, 0xff, v3
	v_ashrrev_i32_e32 v3, 8, v3
	v_add_u32_e32 v2, v3, v2
	s_waitcnt lgkmcnt(0)
	s_barrier
	v_mov_b32_e32 v3, v19
	v_add_u32_e32 v3, 0xff, v3
	v_ashrrev_i32_e32 v3, 8, v3
	v_add_u32_e32 v2, v3, v2
	s_nop 0
	v_readfirstlane_b32 s38, v2
	v_mov_b32_e32 v2, v0
	s_nop 0
	v_cmp_gt_i32_e32 vcc, s38, v2
	s_and_saveexec_b64 s[10:11], vcc
	s_cbranch_execz .LBB0_929
	v_lshlrev_b32_e32 v3, 8, v2
	v_readlane_b32 s3, v255, 0
	v_sub_u32_e32 v4, 0, v3
	s_mov_b64 s[12:13], 0
	v_lshl_add_u32 v5, v2, 3, s3
.LBB0_928:
	v_cmp_lt_i32_e32 vcc, -1, v2
	v_mov_b32_e32 v6, v12
	s_nop 0
	v_cndmask_b32_e32 v7, 0, v6, vcc
	v_add_u32_e32 v6, 0xff, v6
	v_ashrrev_i32_e32 v6, 8, v6
	v_cmp_le_i32_e32 vcc, v6, v2
	v_mov_b32_e32 v8, v13
	s_nop 0
	v_cndmask_b32_e32 v7, v7, v8, vcc
	v_add_u32_e32 v8, 0xff, v8
	v_ashrrev_i32_e32 v8, 8, v8
	v_cndmask_b32_e32 v9, 0, v6, vcc
	v_add_u32_e32 v6, v8, v6
	v_cndmask_b32_e64 v10, 0, 1, vcc
	v_cmp_gt_i32_e32 vcc, v6, v2
	s_nop 1
	v_cndmask_b32_e32 v9, v6, v9, vcc
	v_cndmask_b32_e32 v10, 2, v10, vcc
	v_mov_b32_e32 v8, v14
	v_cndmask_b32_e32 v7, v8, v7, vcc
	v_add_u32_e32 v8, 0xff, v8
	v_ashrrev_i32_e32 v8, 8, v8
	v_add_u32_e32 v6, v8, v6
	v_cmp_gt_i32_e32 vcc, v6, v2
	s_nop 1
	v_cndmask_b32_e32 v9, v6, v9, vcc
	v_cndmask_b32_e32 v10, 3, v10, vcc
	v_mov_b32_e32 v8, v15
	v_cndmask_b32_e32 v7, v8, v7, vcc
	v_add_u32_e32 v8, 0xff, v8
	v_ashrrev_i32_e32 v8, 8, v8
	v_add_u32_e32 v6, v8, v6
	v_cmp_gt_i32_e32 vcc, v6, v2
	s_nop 1
	v_cndmask_b32_e32 v9, v6, v9, vcc
	v_cndmask_b32_e32 v10, 4, v10, vcc
	v_mov_b32_e32 v8, v16
	v_cndmask_b32_e32 v7, v8, v7, vcc
	v_add_u32_e32 v8, 0xff, v8
	v_ashrrev_i32_e32 v8, 8, v8
	v_add_u32_e32 v6, v8, v6
	v_cmp_gt_i32_e32 vcc, v6, v2
	s_nop 1
	v_cndmask_b32_e32 v9, v6, v9, vcc
	v_cndmask_b32_e32 v10, 5, v10, vcc
	v_mov_b32_e32 v8, v17
	v_cndmask_b32_e32 v7, v8, v7, vcc
	v_add_u32_e32 v8, 0xff, v8
	v_ashrrev_i32_e32 v8, 8, v8
	v_add_u32_e32 v6, v8, v6
	v_cmp_gt_i32_e32 vcc, v6, v2
	s_nop 1
	v_cndmask_b32_e32 v9, v6, v9, vcc
	v_cndmask_b32_e32 v10, 6, v10, vcc
	v_mov_b32_e32 v8, v18
	v_cndmask_b32_e32 v7, v8, v7, vcc
	v_add_u32_e32 v8, 0xff, v8
	v_ashrrev_i32_e32 v8, 8, v8
	v_add_u32_e32 v6, v8, v6
	v_cmp_gt_i32_e32 vcc, v6, v2
	v_add_u32_e32 v2, 0x200, v2
	s_nop 0
	v_cndmask_b32_e32 v6, v6, v9, vcc
	v_lshlrev_b32_e32 v6, 8, v6
	v_cndmask_b32_e32 v9, 7, v10, vcc
	v_mov_b32_e32 v8, v19
	v_cndmask_b32_e32 v8, v8, v7, vcc
	v_sub_u32_e32 v7, v3, v6
	v_add3_u32 v6, v8, v6, v4
	v_min_i32_e32 v6, 0x100, v6
	v_cmp_le_i32_e32 vcc, s38, v2
	v_lshl_add_u32 v6, v6, 4, v9
	v_add_u32_e32 v8, -4, v5
	v_add_u32_e32 v3, 0x20000, v3
	v_add_u32_e32 v4, 0xfffe0000, v4
	v_add_u32_e32 v5, 0x1000, v5
	s_or_b64 s[12:13], vcc, s[12:13]
	ds_write_b64 v8, v[6:7]
	s_andn2_b64 exec, exec, s[12:13]
	s_cbranch_execnz .LBB0_928

;     ...
;         if (!has_next) break;
; #pragma unroll
;         for (int a = 0; a < 2; ++a)
; #pragma unroll
;             for (int b = 0; b < 2; ++b)
; #pragma unroll
;                 for (int m = 0; m < 4; ++m)
; #pragma unroll
;                     for (int n = 0; n < 2; ++n) acc[a][b][m][n] = (f32x4){0.f, 0.f, 0.f, 0.f};
;         cur = nxt; cB = nB; ++ui;
.LBB0_968:
	v_mov_b32_e32 v38, 0
	s_waitcnt lgkmcnt(0)
	v_mov_b32_e32 v172, v37
	v_mov_b32_e32 v174, v36
	s_mov_b32 s50, s56
	s_mov_b32 s48, s26
	s_mov_b32 s67, s6
	s_andn2_b64 vcc, exec, s[38:39]
	v_mov_b64_e32 v[6:7], v[176:177]
	s_cbranch_vccz .LBB0_1014

;     __device__ __forceinline__ unsigned arow(const Unit& u, int r) const { return (unsigned)(u.pm * 256 + r); }
;     __device__ __forceinline__ unsigned arow(const Unit& u, int r) const {
;         if (!gatherA) return (unsigned)(u.pm * 256 + r);
;         if (!moe) return (unsigned)(u.aux + r);
;         return (r < u.cnt) ? ((unsigned)list[(size_t)u.e * M + u.aux + r] >> 1) : 0u;
;     }
;     ...
; #pragma unroll
;         for (int a = 0; a < 2; ++a)
; #pragma unroll
;             for (int b = 0; b < 2; ++b)
; #pragma unroll
;                 for (int m = 0; m < 4; ++m)
; #pragma unroll
;                     for (int n = 0; n < 2; ++n) acc[a][b][m][n] = (f32x4){0.f, 0.f, 0.f, 0.f};
.LBB0_977:
	v_cndmask_b32_e64 v2, 0, 1, s[42:43]
	v_cmp_ne_u32_e64 s[40:41], 1, v2
	s_andn2_b64 vcc, exec, s[42:43]
	v_mov_b64_e32 v[176:177], v[6:7]
	v_mov_b32_e32 v2, v34
	v_mov_b32_e32 v3, v35
	v_mov_b32_e32 v4, v36
	v_mov_b32_e32 v5, v37
	s_cbranch_vccnz .Lmy_gu_zero_last
	s_ashr_i32 s55, s54, 31
	s_ashr_i32 s59, s58, 31
	s_lshl_b64 s[12:13], s[54:55], 18
	s_add_u32 s7, s61, s12
	s_addc_u32 s24, s62, s13
	s_lshl_b64 s[12:13], s[58:59], 2
	s_add_u32 s12, s7, s12
	s_addc_u32 s13, s24, s13
	s_mov_b64 s[24:25], -1
	s_and_b64 vcc, exec, s[46:47]
	s_cbranch_vccz .LBB0_994
	v_lshl_add_u64 v[8:9], v[168:169], 2, s[12:13]
	v_cmp_gt_i32_e32 vcc, s49, v168
	v_mov_b32_e32 v2, 0
	s_and_saveexec_b64 s[24:25], vcc
	global_load_dword v2, v[8:9], off
	s_or_b64 exec, exec, s[24:25]
	v_cmp_gt_i32_e32 vcc, s49, v194
	v_mov_b32_e32 v3, 0
	s_and_saveexec_b64 s[24:25], vcc
	global_load_dword v3, v[8:9], off offset:256
	s_or_b64 exec, exec, s[24:25]
	v_cmp_gt_i32_e32 vcc, s49, v195
	v_mov_b32_e32 v4, 0
	s_and_saveexec_b64 s[24:25], vcc
	global_load_dword v4, v[8:9], off offset:512
	s_or_b64 exec, exec, s[24:25]
	v_cmp_gt_i32_e32 vcc, s49, v204
	v_mov_b32_e32 v5, 0
	s_and_saveexec_b64 s[24:25], vcc
	global_load_dword v5, v[8:9], off offset:768
	s_or_b64 exec, exec, s[24:25]
	v_mov_b32_e32 v39, v38
	v_mov_b32_e32 v40, v38
	v_mov_b32_e32 v41, v38
	v_mov_b32_e32 v42, v38
	v_mov_b32_e32 v43, v38
	v_mov_b32_e32 v44, v38
	v_mov_b32_e32 v45, v38
	v_mov_b32_e32 v46, v38
	v_mov_b32_e32 v47, v38
	v_mov_b32_e32 v48, v38
	v_mov_b32_e32 v49, v38
	v_mov_b32_e32 v50, v38
	v_mov_b32_e32 v51, v38
	v_mov_b32_e32 v52, v38
	v_mov_b32_e32 v53, v38
	v_mov_b32_e32 v54, v38
	v_mov_b32_e32 v55, v38
	v_mov_b32_e32 v56, v38
	v_mov_b32_e32 v57, v38
	v_mov_b32_e32 v58, v38
	v_mov_b32_e32 v59, v38
	v_mov_b32_e32 v60, v38
	v_mov_b32_e32 v61, v38
	v_mov_b32_e32 v62, v38
	v_mov_b32_e32 v63, v38
	v_mov_b32_e32 v64, v38
	v_mov_b32_e32 v65, v38
	v_mov_b32_e32 v68, v38
	v_mov_b32_e32 v69, v38
	v_mov_b32_e32 v70, v38
	v_mov_b32_e32 v71, v38
	v_mov_b32_e32 v72, v38
	v_mov_b32_e32 v73, v38
	v_mov_b32_e32 v74, v38
	v_mov_b32_e32 v75, v38
	v_mov_b32_e32 v76, v38
	v_mov_b32_e32 v77, v38
	v_mov_b32_e32 v78, v38
	v_mov_b32_e32 v79, v38
	v_mov_b32_e32 v80, v38
	v_mov_b32_e32 v81, v38
	v_mov_b32_e32 v82, v38
	v_mov_b32_e32 v83, v38
	v_mov_b32_e32 v84, v38
	v_mov_b32_e32 v85, v38
	v_mov_b32_e32 v86, v38
	v_mov_b32_e32 v87, v38
	v_mov_b32_e32 v88, v38
	v_mov_b32_e32 v89, v38
	v_mov_b32_e32 v90, v38
	v_mov_b32_e32 v91, v38
	v_mov_b32_e32 v92, v38
	v_mov_b32_e32 v93, v38
	v_mov_b32_e32 v94, v38
	v_mov_b32_e32 v95, v38
	v_mov_b32_e32 v96, v38
	v_mov_b32_e32 v97, v38
	v_mov_b32_e32 v98, v38
	v_mov_b32_e32 v99, v38
	v_mov_b32_e32 v100, v38
	v_mov_b32_e32 v101, v38
	v_mov_b32_e32 v102, v38
	v_mov_b32_e32 v103, v38
	v_mov_b32_e32 v104, v38
	v_mov_b32_e32 v105, v38
	v_mov_b32_e32 v106, v38
	v_mov_b32_e32 v107, v38
	v_mov_b32_e32 v108, v38
	v_mov_b32_e32 v109, v38
	v_mov_b32_e32 v110, v38
	v_mov_b32_e32 v111, v38
	v_mov_b32_e32 v112, v38
	v_mov_b32_e32 v113, v38
	v_mov_b32_e32 v114, v38
	v_mov_b32_e32 v115, v38
	v_mov_b32_e32 v116, v38
	v_mov_b32_e32 v117, v38
	v_mov_b32_e32 v118, v38
	v_mov_b32_e32 v119, v38
	v_mov_b32_e32 v120, v38
	v_mov_b32_e32 v121, v38
	v_mov_b32_e32 v122, v38
	v_mov_b32_e32 v123, v38
	v_mov_b32_e32 v124, v38
	v_mov_b32_e32 v125, v38
	v_mov_b32_e32 v126, v38
	v_mov_b32_e32 v127, v38
	v_mov_b32_e32 v128, v38
	v_mov_b32_e32 v129, v38
	v_mov_b32_e32 v130, v38
	v_mov_b32_e32 v131, v38
	v_mov_b32_e32 v132, v38
	v_mov_b32_e32 v133, v38
	v_mov_b32_e32 v134, v38
	v_mov_b32_e32 v135, v38
	v_mov_b32_e32 v136, v38
	v_mov_b32_e32 v137, v38
	v_mov_b32_e32 v138, v38
	v_mov_b32_e32 v139, v38
	v_mov_b32_e32 v140, v38
	v_mov_b32_e32 v141, v38
	v_mov_b32_e32 v142, v38
	v_mov_b32_e32 v143, v38
	v_mov_b32_e32 v144, v38
	v_mov_b32_e32 v145, v38
	v_mov_b32_e32 v146, v38
	v_mov_b32_e32 v147, v38
	v_mov_b32_e32 v148, v38
	v_mov_b32_e32 v149, v38
	v_mov_b32_e32 v150, v38
	v_mov_b32_e32 v151, v38
	v_mov_b32_e32 v152, v38
	v_mov_b32_e32 v153, v38
	v_mov_b32_e32 v154, v38
	v_mov_b32_e32 v155, v38
	v_mov_b32_e32 v156, v38
	v_mov_b32_e32 v157, v38
	v_mov_b32_e32 v158, v38
	v_mov_b32_e32 v159, v38
	v_mov_b32_e32 v160, v38
	v_mov_b32_e32 v161, v38
	v_mov_b32_e32 v162, v38
	v_mov_b32_e32 v163, v38
	v_mov_b32_e32 v164, v38
	v_mov_b32_e32 v165, v38
	v_mov_b32_e32 v166, v38
	v_mov_b32_e32 v167, v38
	s_waitcnt vmcnt(0)
	v_lshrrev_b32_e32 v2, 1, v2
	v_lshrrev_b32_e32 v3, 1, v3
	v_lshrrev_b32_e32 v4, 1, v4
	v_lshrrev_b32_e32 v5, 1, v5
	s_branch .LBB0_1002
; #define G_VOA(dst, u) do { _Pragma("unroll") for (int h = 0; h < 2; ++h) _Pragma("unroll") for (int i = 0; i < 2; ++i) dst[h][i] = (S.arow(u, h * HALF + R0 + 64 * i) * (unsigned)K + (unsigned)C0) * 2u; } while (0)
;     ...
;         { unsigned nvo[2][2];
;           if (has_next) { G_VOA(nvo, nxt); nB = (const char*)S.bbase(nxt) + (size_t)nxt.pn * tstep; }
;           else {
; #pragma unroll
;             for (int h = 0; h < 2; ++h)
; #pragma unroll
;                 for (int i = 0; i < 2; ++i) nvo[h][i] = vo[h][i];
;           }
;           *nvo_l = (u32x4){nvo[0][0], nvo[0][1], nvo[1][0], nvo[1][1]}; }
;     ...
; #pragma unroll
;         for (int a = 0; a < 2; ++a)
; #pragma unroll
;             for (int b = 0; b < 2; ++b)
; #pragma unroll
;                 for (int m = 0; m < 4; ++m)
; #pragma unroll
;                     for (int n = 0; n < 2; ++n) acc[a][b][m][n] = (f32x4){0.f, 0.f, 0.f, 0.f};
.Lmy_gu_zero_last:
	v_mov_b32_e32 v39, v38
	v_mov_b32_e32 v40, v38
	v_mov_b32_e32 v41, v38
	v_mov_b32_e32 v42, v38
	v_mov_b32_e32 v43, v38
	v_mov_b32_e32 v44, v38
	v_mov_b32_e32 v45, v38
	v_mov_b32_e32 v46, v38
	v_mov_b32_e32 v47, v38
	v_mov_b32_e32 v48, v38
	v_mov_b32_e32 v49, v38
	v_mov_b32_e32 v50, v38
	v_mov_b32_e32 v51, v38
	v_mov_b32_e32 v52, v38
	v_mov_b32_e32 v53, v38
	v_mov_b32_e32 v54, v38
	v_mov_b32_e32 v55, v38
	v_mov_b32_e32 v56, v38
	v_mov_b32_e32 v57, v38
	v_mov_b32_e32 v58, v38
	v_mov_b32_e32 v59, v38
	v_mov_b32_e32 v60, v38
	v_mov_b32_e32 v61, v38
	v_mov_b32_e32 v62, v38
	v_mov_b32_e32 v63, v38
	v_mov_b32_e32 v64, v38
	v_mov_b32_e32 v65, v38
	v_mov_b32_e32 v68, v38
	v_mov_b32_e32 v69, v38
	v_mov_b32_e32 v70, v38
	v_mov_b32_e32 v71, v38
	v_mov_b32_e32 v72, v38
	v_mov_b32_e32 v73, v38
	v_mov_b32_e32 v74, v38
	v_mov_b32_e32 v75, v38
	v_mov_b32_e32 v76, v38
	v_mov_b32_e32 v77, v38
	v_mov_b32_e32 v78, v38
	v_mov_b32_e32 v79, v38
	v_mov_b32_e32 v80, v38
	v_mov_b32_e32 v81, v38
	v_mov_b32_e32 v82, v38
	v_mov_b32_e32 v83, v38
	v_mov_b32_e32 v84, v38
	v_mov_b32_e32 v85, v38
	v_mov_b32_e32 v86, v38
	v_mov_b32_e32 v87, v38
	v_mov_b32_e32 v88, v38
	v_mov_b32_e32 v89, v38
	v_mov_b32_e32 v90, v38
	v_mov_b32_e32 v91, v38
	v_mov_b32_e32 v92, v38
	v_mov_b32_e32 v93, v38
	v_mov_b32_e32 v94, v38
	v_mov_b32_e32 v95, v38
	v_mov_b32_e32 v96, v38
	v_mov_b32_e32 v97, v38
	v_mov_b32_e32 v98, v38
	v_mov_b32_e32 v99, v38
	v_mov_b32_e32 v100, v38
	v_mov_b32_e32 v101, v38
	v_mov_b32_e32 v102, v38
	v_mov_b32_e32 v103, v38
	v_mov_b32_e32 v104, v38
	v_mov_b32_e32 v105, v38
	v_mov_b32_e32 v106, v38
	v_mov_b32_e32 v107, v38
	v_mov_b32_e32 v108, v38
	v_mov_b32_e32 v109, v38
	v_mov_b32_e32 v110, v38
	v_mov_b32_e32 v111, v38
	v_mov_b32_e32 v112, v38
	v_mov_b32_e32 v113, v38
	v_mov_b32_e32 v114, v38
	v_mov_b32_e32 v115, v38
	v_mov_b32_e32 v116, v38
	v_mov_b32_e32 v117, v38
	v_mov_b32_e32 v118, v38
	v_mov_b32_e32 v119, v38
	v_mov_b32_e32 v120, v38
	v_mov_b32_e32 v121, v38
	v_mov_b32_e32 v122, v38
	v_mov_b32_e32 v123, v38
	v_mov_b32_e32 v124, v38
	v_mov_b32_e32 v125, v38
	v_mov_b32_e32 v126, v38
	v_mov_b32_e32 v127, v38
	v_mov_b32_e32 v128, v38
	v_mov_b32_e32 v129, v38
	v_mov_b32_e32 v130, v38
	v_mov_b32_e32 v131, v38
	v_mov_b32_e32 v132, v38
	v_mov_b32_e32 v133, v38
	v_mov_b32_e32 v134, v38
	v_mov_b32_e32 v135, v38
	v_mov_b32_e32 v136, v38
	v_mov_b32_e32 v137, v38
	v_mov_b32_e32 v138, v38
	v_mov_b32_e32 v139, v38
	v_mov_b32_e32 v140, v38
	v_mov_b32_e32 v141, v38
	v_mov_b32_e32 v142, v38
	v_mov_b32_e32 v143, v38
	v_mov_b32_e32 v144, v38
	v_mov_b32_e32 v145, v38
	v_mov_b32_e32 v146, v38
	v_mov_b32_e32 v147, v38
	v_mov_b32_e32 v148, v38
	v_mov_b32_e32 v149, v38
	v_mov_b32_e32 v150, v38
	v_mov_b32_e32 v151, v38
	v_mov_b32_e32 v152, v38
	v_mov_b32_e32 v153, v38
	v_mov_b32_e32 v154, v38
	v_mov_b32_e32 v155, v38
	v_mov_b32_e32 v156, v38
	v_mov_b32_e32 v157, v38
	v_mov_b32_e32 v158, v38
	v_mov_b32_e32 v159, v38
	v_mov_b32_e32 v160, v38
	v_mov_b32_e32 v161, v38
	v_mov_b32_e32 v162, v38
	v_mov_b32_e32 v163, v38
	v_mov_b32_e32 v164, v38
	v_mov_b32_e32 v165, v38
	v_mov_b32_e32 v166, v38
	v_mov_b32_e32 v167, v38
	s_branch .LBB0_1003
.LBB0_994:
	v_add_u32_e32 v2, s58, v168
	v_add_u32_e32 v3, s58, v194
	v_add_u32_e32 v4, s58, v195
	v_add_u32_e32 v5, s58, v204
	v_mov_b32_e32 v39, v38
	v_mov_b32_e32 v40, v38
	v_mov_b32_e32 v41, v38
	v_mov_b32_e32 v42, v38
	v_mov_b32_e32 v43, v38
	v_mov_b32_e32 v44, v38
	v_mov_b32_e32 v45, v38
	v_mov_b32_e32 v46, v38
	v_mov_b32_e32 v47, v38
	v_mov_b32_e32 v48, v38
	v_mov_b32_e32 v49, v38
	v_mov_b32_e32 v50, v38
	v_mov_b32_e32 v51, v38
	v_mov_b32_e32 v52, v38
	v_mov_b32_e32 v53, v38
	v_mov_b32_e32 v54, v38
	v_mov_b32_e32 v55, v38
	v_mov_b32_e32 v56, v38
	v_mov_b32_e32 v57, v38
	v_mov_b32_e32 v58, v38
	v_mov_b32_e32 v59, v38
	v_mov_b32_e32 v60, v38
	v_mov_b32_e32 v61, v38
	v_mov_b32_e32 v62, v38
	v_mov_b32_e32 v63, v38
	v_mov_b32_e32 v64, v38
	v_mov_b32_e32 v65, v38
	v_mov_b32_e32 v68, v38
	v_mov_b32_e32 v69, v38
	v_mov_b32_e32 v70, v38
	v_mov_b32_e32 v71, v38
	v_mov_b32_e32 v72, v38
	v_mov_b32_e32 v73, v38
	v_mov_b32_e32 v74, v38
	v_mov_b32_e32 v75, v38
	v_mov_b32_e32 v76, v38
	v_mov_b32_e32 v77, v38
	v_mov_b32_e32 v78, v38
	v_mov_b32_e32 v79, v38
	v_mov_b32_e32 v80, v38
	v_mov_b32_e32 v81, v38
	v_mov_b32_e32 v82, v38
	v_mov_b32_e32 v83, v38
	v_mov_b32_e32 v84, v38
	v_mov_b32_e32 v85, v38
	v_mov_b32_e32 v86, v38
	v_mov_b32_e32 v87, v38
	v_mov_b32_e32 v88, v38
	v_mov_b32_e32 v89, v38
	v_mov_b32_e32 v90, v38
	v_mov_b32_e32 v91, v38
	v_mov_b32_e32 v92, v38
	v_mov_b32_e32 v93, v38
	v_mov_b32_e32 v94, v38
	v_mov_b32_e32 v95, v38
	v_mov_b32_e32 v96, v38
	v_mov_b32_e32 v97, v38
	v_mov_b32_e32 v98, v38
	v_mov_b32_e32 v99, v38
	v_mov_b32_e32 v100, v38
	v_mov_b32_e32 v101, v38
	v_mov_b32_e32 v102, v38
	v_mov_b32_e32 v103, v38
	v_mov_b32_e32 v104, v38
	v_mov_b32_e32 v105, v38
	v_mov_b32_e32 v106, v38
	v_mov_b32_e32 v107, v38
	v_mov_b32_e32 v108, v38
	v_mov_b32_e32 v109, v38
	v_mov_b32_e32 v110, v38
	v_mov_b32_e32 v111, v38
	v_mov_b32_e32 v112, v38
	v_mov_b32_e32 v113, v38
	v_mov_b32_e32 v114, v38
	v_mov_b32_e32 v115, v38
	v_mov_b32_e32 v116, v38
	v_mov_b32_e32 v117, v38
	v_mov_b32_e32 v118, v38
	v_mov_b32_e32 v119, v38
	v_mov_b32_e32 v120, v38
	v_mov_b32_e32 v121, v38
	v_mov_b32_e32 v122, v38
	v_mov_b32_e32 v123, v38
	v_mov_b32_e32 v124, v38
	v_mov_b32_e32 v125, v38
	v_mov_b32_e32 v126, v38
	v_mov_b32_e32 v127, v38
	v_mov_b32_e32 v128, v38
	v_mov_b32_e32 v129, v38
	v_mov_b32_e32 v130, v38
	v_mov_b32_e32 v131, v38
	v_mov_b32_e32 v132, v38
	v_mov_b32_e32 v133, v38
	v_mov_b32_e32 v134, v38
	v_mov_b32_e32 v135, v38
	v_mov_b32_e32 v136, v38
	v_mov_b32_e32 v137, v38
	v_mov_b32_e32 v138, v38
	v_mov_b32_e32 v139, v38
	v_mov_b32_e32 v140, v38
	v_mov_b32_e32 v141, v38
	v_mov_b32_e32 v142, v38
	v_mov_b32_e32 v143, v38
	v_mov_b32_e32 v144, v38
	v_mov_b32_e32 v145, v38
	v_mov_b32_e32 v146, v38
	v_mov_b32_e32 v147, v38
	v_mov_b32_e32 v148, v38
	v_mov_b32_e32 v149, v38
	v_mov_b32_e32 v150, v38
	v_mov_b32_e32 v151, v38
	v_mov_b32_e32 v152, v38
	v_mov_b32_e32 v153, v38
	v_mov_b32_e32 v154, v38
	v_mov_b32_e32 v155, v38
	v_mov_b32_e32 v156, v38
	v_mov_b32_e32 v157, v38
	v_mov_b32_e32 v158, v38
	v_mov_b32_e32 v159, v38
	v_mov_b32_e32 v160, v38
	v_mov_b32_e32 v161, v38
	v_mov_b32_e32 v162, v38
	v_mov_b32_e32 v163, v38
	v_mov_b32_e32 v164, v38
	v_mov_b32_e32 v165, v38
	v_mov_b32_e32 v166, v38
	v_mov_b32_e32 v167, v38
